# scan loop VMEM balance 4/3/4/3 again, loop head placed at 4 mod 8 like the baseline's (placement test)
# baseline (speedup 1.0000x reference)
; #define LDS_BARRIER() do { asm volatile("s_waitcnt lgkmcnt(0)" ::: "memory"); __builtin_amdgcn_s_barrier(); asm volatile("" ::: "memory"); } while (0)
; #define MFMA16(a, b, c) __builtin_amdgcn_mfma_f32_16x16x32_bf16(a, b, c, 0, 0, 0)
; __device__ __forceinline__ f32x4 up_bf4(u32x2 u) { return (f32x4){bf_lo(u.x), bf_hi(u.x), bf_lo(u.y), bf_hi(u.y)}; }
; __device__ __forceinline__ void seq_item(const Params& p, unsigned char* shm, int row0, int nchunks, int h, const float* S0, float* Sout) {
;     ...
;         *(u32x4*)(p.Z + (size_t)(row0 + ci * 64 + crow) * LDZ + ZC_S + h * 64 + cseg) = *(const u32x4*)(Sb + crow * LD + cseg);
;         const bf16x8 w10 = ldfrag(W1s, LD, 16 * m, 0, fr, fq), w11 = ldfrag(W1s, LD, 16 * m, 32, fr, fq);
; #pragma unroll
;         for (int q = 0; q < 2; ++q) {
;             const int v = 16 * (nv0 + q) + fr;
;             f32x4 acc = up_bf4(*(const u32x2*)(U0s + v * LD + c0));
;             acc = MFMA16(w10, ldfrag(Sb, LD, 16 * (nv0 + q), 0, fr, fq), acc);
;             acc = MFMA16(w11, ldfrag(Sb, LD, 16 * (nv0 + q), 32, fr, fq), acc);
;             *(u32x2*)(UT + v * LD + c0) = pk_bf4(acc);
;         }
;         LDS_BARRIER();
;         *(u32x4*)(p.UTG + cb + crow * 64 + cseg) = *(const u32x4*)(UT + crow * LD + cseg);
;         const bf16x8 bp0 = ldfrag(BPs, LD, 16 * m, 0, fr, fq), bp1 = ldfrag(BPs, LD, 16 * m, 32, fr, fq);
;         const f32x4 gc = *(const f32x4*)(GCs + c0);
; #pragma unroll
;         for (int q = 0; q < 2; ++q) {
;             const int v = 16 * (nv0 + q) + fr;
;             f32x4 acc = S[q] * gc + up_bf4(*(const u32x2*)(VKs + v * LD + c0));
;             acc = MFMA16(bp0, ldfrag(UT, LD, 16 * (nv0 + q), 0, fr, fq), acc);
;             acc = MFMA16(bp1, ldfrag(UT, LD, 16 * (nv0 + q), 32, fr, fq), acc);
;             S[q] = acc;
;         }
;     };
;     Stage A, B;
;     gload(0, A); gload(min(1, last), B);
;     park(0, A); park(1, B);
;     gload(min(2, last), A);
;     int scur = 0, spark = 2;
;     for (int ci = 0; ci < nchunks; ci += 2) {
;         gload(min(ci + 3, last), B);
;         body(ci, scur, spark, A);
;         scur = scur == 2 ? 0 : scur + 1; spark = spark == 2 ? 0 : spark + 1;
;         if (ci + 1 >= nchunks) break;
;         gload(min(ci + 4, last), A);
;         body(ci + 1, scur, spark, B);
;         scur = scur == 2 ? 0 : scur + 1; spark = spark == 2 ? 0 : spark + 1;
;     }
.LBB0_437:
	s_or_b64 exec, exec, s[22:23]
	s_add_i32 s22, s28, 1
	s_cmp_lg_u32 s28, 2
	s_cselect_b32 s22, s22, 0
	s_mul_i32 s23, s22, 0x9100
	s_add_i32 s23, s23, 0
	v_add3_u32 v80, s23, v65, v69
	v_add3_u32 v81, s23, v70, v71
	ds_read_b64 v[38:39], v81 offset:36864
	s_waitcnt vmcnt(7)
	ds_read_b128 v[28:31], v80 offset:18496
	ds_read_b128 v[32:35], v80 offset:18432
	ds_read_b128 v[40:43], v60
	ds_read_b128 v[44:47], v66
	ds_read_b128 v[70:73], v66 offset:64
	ds_read_b128 v[74:77], v67 offset:64
	s_waitcnt lgkmcnt(6)
	v_lshlrev_b32_e32 v36, 16, v38
	v_and_b32_e32 v37, 0xffff0000, v38
	v_lshlrev_b32_e32 v38, 16, v39
	v_and_b32_e32 v39, 0xffff0000, v39
	v_add_u32_e32 v82, 64, v68
	v_mov_b64_e32 v[78:79], s[20:21]
	s_waitcnt lgkmcnt(2)
	v_mfma_f32_16x16x32_bf16 v[36:39], v[32:35], v[44:47], v[36:39]
	ds_read_b128 v[44:47], v67
	v_mad_i64_i32 v[78:79], s[20:21], v82, s27, v[78:79]
	s_waitcnt lgkmcnt(2)
	v_mfma_f32_16x16x32_bf16 v[36:39], v[28:31], v[70:73], v[36:39]
	v_add_u32_e32 v68, 0x80, v68
	v_lshl_add_u64 v[56:57], v[56:57], 0, s[6:7]
	s_add_i32 s86, s26, 2
	s_min_u32 s86, s86, 0x7c
	s_lshl_b32 s86, s86, 4
	s_add_i32 s86, s24, s86
	s_ashr_i32 s87, s86, 31
	s_lshl_b64 s[88:89], s[86:87], 12
	v_lshl_add_u64 v[190:191], s[88:89], 0, v[52:53]
	v_lshlrev_b64 v[190:191], 1, v[190:191]
	v_lshl_add_u64 v[192:193], s[12:13], 0, v[190:191]
	global_load_dwordx4 v[200:203], v[192:193], off
	v_lshl_add_u64 v[194:195], s[14:15], 0, v[190:191]
	global_load_dwordx4 v[204:207], v[194:195], off
	v_lshl_add_u64 v[192:193], s[16:17], 0, v[190:191]
	global_load_dwordx4 v[208:211], v[192:193], off
	s_nop 5
	v_cvt_pk_bf16_f32 v36, v36, v37
	v_cvt_pk_bf16_f32 v37, v38, v39
	ds_write_b64 v63, v[36:37] offset:9216
	ds_read_b64 v[38:39], v81 offset:39168
	v_lshl_add_u64 v[36:37], v[78:79], 0, s[4:5]
	v_lshl_add_u64 v[70:71], v[36:37], 0, v[48:49]
	v_add_co_u32_e32 v70, vcc, 0x1000, v70
	s_waitcnt lgkmcnt(0)
	v_lshlrev_b32_e32 v36, 16, v38
	v_and_b32_e32 v37, 0xffff0000, v38
	v_lshlrev_b32_e32 v38, 16, v39
	v_and_b32_e32 v39, 0xffff0000, v39
	v_addc_co_u32_e32 v71, vcc, 0, v71, vcc
	s_nop 0
	v_mfma_f32_16x16x32_bf16 v[32:35], v[32:35], v[44:47], v[36:39]
	global_store_dwordx4 v[70:71], v[40:43], off offset:2048
	v_mfma_f32_16x16x32_bf16 v[28:31], v[28:31], v[74:77], v[32:35]
	s_nop 0
	v_lshl_add_u32 v36, v50, 2, s23
	s_nop 5
	v_cvt_pk_bf16_f32 v28, v28, v29
	v_cvt_pk_bf16_f32 v29, v30, v31
	ds_write_b64 v64, v[28:29] offset:9216
	s_waitcnt lgkmcnt(0)
	s_barrier
	ds_read_b64 v[40:41], v81 offset:46080
	ds_read_b128 v[28:31], v80 offset:27712
	ds_read_b128 v[32:35], v80 offset:27648
	ds_read_b128 v[36:39], v36 offset:55296
	s_waitcnt lgkmcnt(3)
	v_lshlrev_b32_e32 v44, 16, v40
	v_and_b32_e32 v45, 0xffff0000, v40
	v_lshlrev_b32_e32 v46, 16, v41
	v_and_b32_e32 v47, 0xffff0000, v41
	ds_read_b128 v[40:43], v66 offset:9216
	ds_read_b64 v[74:75], v81 offset:48384
	s_waitcnt lgkmcnt(2)
	v_pk_fma_f32 v[26:27], v[26:27], v[38:39], v[46:47]
	v_pk_fma_f32 v[24:25], v[24:25], v[36:37], v[44:45]
	ds_read_b128 v[44:47], v67 offset:9280
	s_waitcnt lgkmcnt(2)
	v_mfma_f32_16x16x32_bf16 v[24:27], v[32:35], v[40:43], v[24:27]
	ds_read_b128 v[40:43], v66 offset:9280
	ds_read_b128 v[70:73], v67 offset:9216
	s_waitcnt lgkmcnt(1)
	v_mfma_f32_16x16x32_bf16 v[24:27], v[28:31], v[40:43], v[24:27]
	v_lshlrev_b32_e32 v40, 16, v74
	v_and_b32_e32 v41, 0xffff0000, v74
	v_lshlrev_b32_e32 v42, 16, v75
	v_and_b32_e32 v43, 0xffff0000, v75
	v_pk_fma_f32 v[22:23], v[22:23], v[38:39], v[42:43]
	v_pk_fma_f32 v[20:21], v[20:21], v[36:37], v[40:41]
	v_lshl_add_u64 v[36:37], s[10:11], 0, v[58:59]
	s_add_i32 s10, s22, 1
	s_waitcnt lgkmcnt(0)
	v_mfma_f32_16x16x32_bf16 v[20:23], v[32:35], v[70:73], v[20:23]
	ds_read_b128 v[32:35], v60 offset:9216
	s_cmp_lg_u32 s22, 2
	s_cselect_b32 s28, s10, 0
	v_mfma_f32_16x16x32_bf16 v[20:23], v[28:31], v[44:47], v[20:23]
	s_add_i32 s10, s29, 1
	s_cmp_lg_u32 s29, 2
	s_cselect_b32 s22, s10, 0
	s_cmpk_lt_u32 s26, 0x7e
	v_lshl_add_u64 v[58:59], v[58:59], 0, s[6:7]
	s_waitcnt lgkmcnt(0)
	global_store_dwordx4 v[36:37], v[32:35], off
	s_cbranch_scc0 .LBB0_442
	s_nop 0
